# grid barrier spin loops: s_sleep 4 instead of s_sleep 1 between polls
# baseline (speedup 1.0000x reference)
; __global__ void __launch_bounds__(512, 2) fwd_megakernel(Params P) {
;     ...
;     grid.sync();
.LBB0_79:
	s_sleep 4
	global_load_dword v2, v0, s[2:3] offset:32 sc1
	s_waitcnt vmcnt(0)
	v_and_b32_e32 v2, 0xffff0000, v2
	v_cmp_ne_u32_e32 vcc, v2, v1
	s_or_b64 s[4:5], vcc, s[4:5]
	s_andn2_b64 exec, exec, s[4:5]
	s_cbranch_execnz .LBB0_79

; __device__ __forceinline__ unsigned xb_ld(unsigned* p)              { return __hip_atomic_load(p, __ATOMIC_RELAXED, __HIP_MEMORY_SCOPE_AGENT); }
; __device__ __forceinline__ void xcd_barrier_complete(unsigned* bar, unsigned x, unsigned& nloc, unsigned& nx) {
;     ...
;     for (;;) {
;         sum = 0u; cnt = 0u; mine = 0u;
; #pragma unroll
;         for (unsigned j = 0; j < 16; ++j) { const unsigned c = xb_ld(&bar[XB_XCNT(j)]); sum += c; cnt += (c > 0u) ? 1u : 0u; mine = (j == x) ? c : mine; }
;         if (sum == G) break;
;         __builtin_amdgcn_s_sleep(1);
;         if ((++sp & 255u) == 0u) { if (xb_ld(&bar[XB_TMO])) break; if (sp > XB_SPIN_CAP) { atomicAdd(&bar[XB_TMO], 1u); break; } }
;     }
.LBB0_207:
	global_load_dword v15, v16, s[74:75] offset:1024 sc1
	s_waitcnt lgkmcnt(0)
	global_load_dword v0, v16, s[74:75] offset:1280 sc1
	global_load_dword v1, v16, s[74:75] offset:1536 sc1
	global_load_dword v2, v16, s[74:75] offset:1792 sc1
	global_load_dword v3, v16, s[74:75] offset:2048 sc1
	global_load_dword v4, v16, s[74:75] offset:2304 sc1
	global_load_dword v5, v16, s[74:75] offset:2560 sc1
	global_load_dword v6, v16, s[74:75] offset:2816 sc1
	global_load_dword v7, v16, s[74:75] offset:3072 sc1
	global_load_dword v8, v16, s[74:75] offset:3328 sc1
	global_load_dword v9, v16, s[74:75] offset:3584 sc1
	global_load_dword v10, v16, s[74:75] offset:3840 sc1
	global_load_dword v11, v16, s[4:5] sc1
	global_load_dword v12, v16, s[6:7] sc1
	global_load_dword v13, v16, s[10:11] sc1
	global_load_dword v14, v16, s[12:13] sc1
	s_mov_b64 s[52:53], -1
	s_mov_b64 s[54:55], -1
	s_waitcnt vmcnt(14)
	v_add_u32_e32 v17, v0, v15
	s_waitcnt vmcnt(13)
	v_add_u32_e32 v17, v17, v1
	s_waitcnt vmcnt(12)
	v_add_u32_e32 v17, v17, v2
	s_waitcnt vmcnt(11)
	v_add_u32_e32 v17, v17, v3
	s_waitcnt vmcnt(10)
	v_add_u32_e32 v17, v17, v4
	s_waitcnt vmcnt(9)
	v_add_u32_e32 v17, v17, v5
	s_waitcnt vmcnt(8)
	v_add_u32_e32 v17, v17, v6
	s_waitcnt vmcnt(7)
	v_add_u32_e32 v17, v17, v7
	s_waitcnt vmcnt(6)
	v_add_u32_e32 v17, v17, v8
	s_waitcnt vmcnt(5)
	v_add_u32_e32 v17, v17, v9
	s_waitcnt vmcnt(4)
	v_add_u32_e32 v17, v17, v10
	s_waitcnt vmcnt(3)
	v_add_u32_e32 v17, v17, v11
	s_waitcnt vmcnt(2)
	v_add_u32_e32 v17, v17, v12
	s_waitcnt vmcnt(1)
	v_add_u32_e32 v17, v17, v13
	s_waitcnt vmcnt(0)
	v_add_u32_e32 v17, v17, v14
	v_cmp_eq_u32_e32 vcc, s33, v17
	s_cbranch_vccnz .LBB0_206
	s_and_b32 s1, s0, 0xff
	s_cmp_eq_u32 s1, 0
	s_mov_b64 s[62:63], -1
	s_sleep 4
	s_cbranch_scc1 .LBB0_211
	s_and_b64 vcc, exec, s[62:63]
	s_cbranch_vccz .LBB0_206

.LBB0_225:
	s_and_b32 s1, s0, 0xff
	s_mov_b64 s[62:63], -1
	s_cmp_lg_u32 s1, 0
	s_mov_b64 s[68:69], -1
	s_sleep 4
	s_cbranch_scc0 .LBB0_228
	s_and_b64 vcc, exec, s[68:69]
	s_cbranch_vccz .LBB0_224

.LBB0_242:
	s_and_b32 s1, s0, 0xff
	s_cmp_lg_u32 s1, 0
	s_mov_b64 s[68:69], -1
	s_sleep 4
	s_cbranch_scc0 .LBB0_245
	s_mov_b64 s[78:79], -1
	s_and_b64 vcc, exec, s[68:69]
	s_cbranch_vccz .LBB0_241

; __device__ __forceinline__ unsigned xb_ld(unsigned* p)              { return __hip_atomic_load(p, __ATOMIC_RELAXED, __HIP_MEMORY_SCOPE_AGENT); }
; __device__ __forceinline__ void xcd_barrier_complete(unsigned* bar, unsigned x, unsigned& nloc, unsigned& nx) {
;     ...
;     for (;;) {
;         sum = 0u; cnt = 0u; mine = 0u;
; #pragma unroll
;         for (unsigned j = 0; j < 16; ++j) { const unsigned c = xb_ld(&bar[XB_XCNT(j)]); sum += c; cnt += (c > 0u) ? 1u : 0u; mine = (j == x) ? c : mine; }
;         if (sum == G) break;
;         __builtin_amdgcn_s_sleep(1);
;         if ((++sp & 255u) == 0u) { if (xb_ld(&bar[XB_TMO])) break; if (sp > XB_SPIN_CAP) { atomicAdd(&bar[XB_TMO], 1u); break; } }
;     }
.LBB0_511:
	global_load_dword v15, v16, s[74:75] offset:1024 sc1
	s_waitcnt lgkmcnt(0)
	global_load_dword v0, v16, s[74:75] offset:1280 sc1
	global_load_dword v1, v16, s[74:75] offset:1536 sc1
	global_load_dword v2, v16, s[74:75] offset:1792 sc1
	global_load_dword v3, v16, s[74:75] offset:2048 sc1
	global_load_dword v4, v16, s[74:75] offset:2304 sc1
	global_load_dword v5, v16, s[74:75] offset:2560 sc1
	global_load_dword v6, v16, s[74:75] offset:2816 sc1
	global_load_dword v7, v16, s[74:75] offset:3072 sc1
	global_load_dword v8, v16, s[74:75] offset:3328 sc1
	global_load_dword v9, v16, s[74:75] offset:3584 sc1
	global_load_dword v10, v16, s[74:75] offset:3840 sc1
	global_load_dword v11, v16, s[4:5] sc1
	global_load_dword v12, v16, s[6:7] sc1
	global_load_dword v13, v16, s[10:11] sc1
	global_load_dword v14, v16, s[52:53] sc1
	s_mov_b64 s[62:63], -1
	s_mov_b64 s[66:67], -1
	s_waitcnt vmcnt(14)
	v_add_u32_e32 v17, v0, v15
	s_waitcnt vmcnt(13)
	v_add_u32_e32 v17, v17, v1
	s_waitcnt vmcnt(12)
	v_add_u32_e32 v17, v17, v2
	s_waitcnt vmcnt(11)
	v_add_u32_e32 v17, v17, v3
	s_waitcnt vmcnt(10)
	v_add_u32_e32 v17, v17, v4
	s_waitcnt vmcnt(9)
	v_add_u32_e32 v17, v17, v5
	s_waitcnt vmcnt(8)
	v_add_u32_e32 v17, v17, v6
	s_waitcnt vmcnt(7)
	v_add_u32_e32 v17, v17, v7
	s_waitcnt vmcnt(6)
	v_add_u32_e32 v17, v17, v8
	s_waitcnt vmcnt(5)
	v_add_u32_e32 v17, v17, v9
	s_waitcnt vmcnt(4)
	v_add_u32_e32 v17, v17, v10
	s_waitcnt vmcnt(3)
	v_add_u32_e32 v17, v17, v11
	s_waitcnt vmcnt(2)
	v_add_u32_e32 v17, v17, v12
	s_waitcnt vmcnt(1)
	v_add_u32_e32 v17, v17, v13
	s_waitcnt vmcnt(0)
	v_add_u32_e32 v17, v17, v14
	v_cmp_eq_u32_e32 vcc, s33, v17
	s_cbranch_vccnz .LBB0_510
	s_and_b32 s1, s0, 0xff
	s_cmp_eq_u32 s1, 0
	s_mov_b64 s[68:69], -1
	s_sleep 4
	s_cbranch_scc1 .LBB0_515
	s_and_b64 vcc, exec, s[68:69]
	s_cbranch_vccz .LBB0_510

.LBB0_529:
	s_and_b32 s1, s0, 0xff
	s_mov_b64 s[68:69], -1
	s_cmp_lg_u32 s1, 0
	s_mov_b64 s[80:81], -1
	s_sleep 4
	s_cbranch_scc0 .LBB0_532
	s_and_b64 vcc, exec, s[80:81]
	s_cbranch_vccz .LBB0_528

.LBB0_546:
	s_and_b32 s1, s0, 0xff
	s_cmp_lg_u32 s1, 0
	s_mov_b64 s[80:81], -1
	s_sleep 4
	s_cbranch_scc0 .LBB0_549
	s_mov_b64 s[82:83], -1
	s_and_b64 vcc, exec, s[80:81]
	s_cbranch_vccz .LBB0_545

; __device__ __forceinline__ unsigned xb_ld(unsigned* p)              { return __hip_atomic_load(p, __ATOMIC_RELAXED, __HIP_MEMORY_SCOPE_AGENT); }
; __device__ __forceinline__ void xcd_barrier_complete(unsigned* bar, unsigned x, unsigned& nloc, unsigned& nx) {
;     ...
;     for (;;) {
;         sum = 0u; cnt = 0u; mine = 0u;
; #pragma unroll
;         for (unsigned j = 0; j < 16; ++j) { const unsigned c = xb_ld(&bar[XB_XCNT(j)]); sum += c; cnt += (c > 0u) ? 1u : 0u; mine = (j == x) ? c : mine; }
;         if (sum == G) break;
;         __builtin_amdgcn_s_sleep(1);
;         if ((++sp & 255u) == 0u) { if (xb_ld(&bar[XB_TMO])) break; if (sp > XB_SPIN_CAP) { atomicAdd(&bar[XB_TMO], 1u); break; } }
;     }
.LBB0_767:
	global_load_dword v15, v16, s[74:75] offset:1024 sc1
	s_waitcnt lgkmcnt(0)
	global_load_dword v0, v16, s[74:75] offset:1280 sc1
	global_load_dword v1, v16, s[74:75] offset:1536 sc1
	global_load_dword v2, v16, s[74:75] offset:1792 sc1
	global_load_dword v3, v16, s[74:75] offset:2048 sc1
	global_load_dword v4, v16, s[74:75] offset:2304 sc1
	global_load_dword v5, v16, s[74:75] offset:2560 sc1
	global_load_dword v6, v16, s[74:75] offset:2816 sc1
	global_load_dword v7, v16, s[74:75] offset:3072 sc1
	global_load_dword v8, v16, s[74:75] offset:3328 sc1
	global_load_dword v9, v16, s[74:75] offset:3584 sc1
	global_load_dword v10, v16, s[74:75] offset:3840 sc1
	global_load_dword v11, v16, s[4:5] sc1
	global_load_dword v12, v16, s[6:7] sc1
	global_load_dword v13, v16, s[8:9] sc1
	global_load_dword v14, v16, s[10:11] sc1
	s_mov_b64 s[62:63], -1
	s_mov_b64 s[66:67], -1
	s_waitcnt vmcnt(14)
	v_add_u32_e32 v17, v0, v15
	s_waitcnt vmcnt(13)
	v_add_u32_e32 v17, v17, v1
	s_waitcnt vmcnt(12)
	v_add_u32_e32 v17, v17, v2
	s_waitcnt vmcnt(11)
	v_add_u32_e32 v17, v17, v3
	s_waitcnt vmcnt(10)
	v_add_u32_e32 v17, v17, v4
	s_waitcnt vmcnt(9)
	v_add_u32_e32 v17, v17, v5
	s_waitcnt vmcnt(8)
	v_add_u32_e32 v17, v17, v6
	s_waitcnt vmcnt(7)
	v_add_u32_e32 v17, v17, v7
	s_waitcnt vmcnt(6)
	v_add_u32_e32 v17, v17, v8
	s_waitcnt vmcnt(5)
	v_add_u32_e32 v17, v17, v9
	s_waitcnt vmcnt(4)
	v_add_u32_e32 v17, v17, v10
	s_waitcnt vmcnt(3)
	v_add_u32_e32 v17, v17, v11
	s_waitcnt vmcnt(2)
	v_add_u32_e32 v17, v17, v12
	s_waitcnt vmcnt(1)
	v_add_u32_e32 v17, v17, v13
	s_waitcnt vmcnt(0)
	v_add_u32_e32 v17, v17, v14
	v_cmp_eq_u32_e32 vcc, s33, v17
	s_cbranch_vccnz .LBB0_766
	s_and_b32 s1, s0, 0xff
	s_cmp_eq_u32 s1, 0
	s_mov_b64 s[68:69], -1
	s_sleep 4
	s_cbranch_scc1 .LBB0_771
	s_and_b64 vcc, exec, s[68:69]
	s_cbranch_vccz .LBB0_766

; __device__ __forceinline__ unsigned xb_ld(unsigned* p)              { return __hip_atomic_load(p, __ATOMIC_RELAXED, __HIP_MEMORY_SCOPE_AGENT); }
; __device__ __forceinline__ void xcd_barrier_complete(unsigned* bar, unsigned x, unsigned& nloc, unsigned& nx) {
;     ...
;     for (;;) {
;         sum = 0u; cnt = 0u; mine = 0u;
; #pragma unroll
;         for (unsigned j = 0; j < 16; ++j) { const unsigned c = xb_ld(&bar[XB_XCNT(j)]); sum += c; cnt += (c > 0u) ? 1u : 0u; mine = (j == x) ? c : mine; }
;         if (sum == G) break;
;         __builtin_amdgcn_s_sleep(1);
;         if ((++sp & 255u) == 0u) { if (xb_ld(&bar[XB_TMO])) break; if (sp > XB_SPIN_CAP) { atomicAdd(&bar[XB_TMO], 1u); break; } }
;     }
.LBB0_1402:
	global_load_dword v15, v16, s[74:75] offset:1024 sc1
	s_waitcnt lgkmcnt(0)
	global_load_dword v0, v16, s[74:75] offset:1280 sc1
	global_load_dword v1, v16, s[74:75] offset:1536 sc1
	global_load_dword v2, v16, s[74:75] offset:1792 sc1
	global_load_dword v3, v16, s[74:75] offset:2048 sc1
	global_load_dword v4, v16, s[74:75] offset:2304 sc1
	global_load_dword v5, v16, s[74:75] offset:2560 sc1
	global_load_dword v6, v16, s[74:75] offset:2816 sc1
	global_load_dword v7, v16, s[74:75] offset:3072 sc1
	global_load_dword v8, v16, s[74:75] offset:3328 sc1
	global_load_dword v9, v16, s[74:75] offset:3584 sc1
	global_load_dword v10, v16, s[74:75] offset:3840 sc1
	global_load_dword v11, v16, s[6:7] sc1
	global_load_dword v12, v16, s[8:9] sc1
	global_load_dword v13, v16, s[10:11] sc1
	global_load_dword v14, v16, s[62:63] sc1
	s_mov_b64 s[66:67], -1
	s_mov_b64 s[68:69], -1
	s_waitcnt vmcnt(14)
	v_add_u32_e32 v17, v0, v15
	s_waitcnt vmcnt(13)
	v_add_u32_e32 v17, v17, v1
	s_waitcnt vmcnt(12)
	v_add_u32_e32 v17, v17, v2
	s_waitcnt vmcnt(11)
	v_add_u32_e32 v17, v17, v3
	s_waitcnt vmcnt(10)
	v_add_u32_e32 v17, v17, v4
	s_waitcnt vmcnt(9)
	v_add_u32_e32 v17, v17, v5
	s_waitcnt vmcnt(8)
	v_add_u32_e32 v17, v17, v6
	s_waitcnt vmcnt(7)
	v_add_u32_e32 v17, v17, v7
	s_waitcnt vmcnt(6)
	v_add_u32_e32 v17, v17, v8
	s_waitcnt vmcnt(5)
	v_add_u32_e32 v17, v17, v9
	s_waitcnt vmcnt(4)
	v_add_u32_e32 v17, v17, v10
	s_waitcnt vmcnt(3)
	v_add_u32_e32 v17, v17, v11
	s_waitcnt vmcnt(2)
	v_add_u32_e32 v17, v17, v12
	s_waitcnt vmcnt(1)
	v_add_u32_e32 v17, v17, v13
	s_waitcnt vmcnt(0)
	v_add_u32_e32 v17, v17, v14
	v_cmp_eq_u32_e32 vcc, s33, v17
	s_cbranch_vccnz .LBB0_1401
	s_and_b32 s1, s0, 0xff
	s_cmp_eq_u32 s1, 0
	s_mov_b64 s[76:77], -1
	s_sleep 4
	s_cbranch_scc1 .LBB0_1406
	s_and_b64 vcc, exec, s[76:77]
	s_cbranch_vccz .LBB0_1401

.LBB0_1420:
	s_and_b32 s1, s0, 0xff
	s_mov_b64 s[76:77], -1
	s_cmp_lg_u32 s1, 0
	s_mov_b64 s[80:81], -1
	s_sleep 4
	s_cbranch_scc0 .LBB0_1423
	s_and_b64 vcc, exec, s[80:81]
	s_cbranch_vccz .LBB0_1419

.LBB0_1837:
	s_and_b32 s1, s0, 0xff
	s_mov_b64 s[68:69], -1
	s_cmp_lg_u32 s1, 0
	s_mov_b64 s[78:79], -1
	s_sleep 4
	s_cbranch_scc0 .LBB0_1840
	s_and_b64 vcc, exec, s[78:79]
	s_cbranch_vccz .LBB0_1836

.LBB0_1854:
	s_and_b32 s1, s0, 0xff
	s_cmp_lg_u32 s1, 0
	s_mov_b64 s[78:79], -1
	s_sleep 4
	s_cbranch_scc0 .LBB0_1857
	s_mov_b64 s[80:81], -1
	s_and_b64 vcc, exec, s[78:79]
	s_cbranch_vccz .LBB0_1853

; __device__ __forceinline__ unsigned xb_ld(unsigned* p)              { return __hip_atomic_load(p, __ATOMIC_RELAXED, __HIP_MEMORY_SCOPE_AGENT); }
; __device__ __forceinline__ void xcd_barrier_complete(unsigned* bar, unsigned x, unsigned& nloc, unsigned& nx) {
;     ...
;     for (;;) {
;         sum = 0u; cnt = 0u; mine = 0u;
; #pragma unroll
;         for (unsigned j = 0; j < 16; ++j) { const unsigned c = xb_ld(&bar[XB_XCNT(j)]); sum += c; cnt += (c > 0u) ? 1u : 0u; mine = (j == x) ? c : mine; }
;         if (sum == G) break;
;         __builtin_amdgcn_s_sleep(1);
;         if ((++sp & 255u) == 0u) { if (xb_ld(&bar[XB_TMO])) break; if (sp > XB_SPIN_CAP) { atomicAdd(&bar[XB_TMO], 1u); break; } }
;     }
.LBB0_2196:
	global_load_dword v15, v16, s[74:75] offset:1024 sc1
	s_waitcnt lgkmcnt(0)
	global_load_dword v0, v16, s[74:75] offset:1280 sc1
	global_load_dword v1, v16, s[74:75] offset:1536 sc1
	global_load_dword v2, v16, s[74:75] offset:1792 sc1
	global_load_dword v3, v16, s[74:75] offset:2048 sc1
	global_load_dword v4, v16, s[74:75] offset:2304 sc1
	global_load_dword v5, v16, s[74:75] offset:2560 sc1
	global_load_dword v6, v16, s[74:75] offset:2816 sc1
	global_load_dword v7, v16, s[74:75] offset:3072 sc1
	global_load_dword v8, v16, s[74:75] offset:3328 sc1
	global_load_dword v9, v16, s[74:75] offset:3584 sc1
	global_load_dword v10, v16, s[74:75] offset:3840 sc1
	global_load_dword v11, v16, s[8:9] sc1
	global_load_dword v12, v16, s[10:11] sc1
	global_load_dword v13, v16, s[54:55] sc1
	global_load_dword v14, v16, s[62:63] sc1
	s_mov_b64 s[66:67], -1
	s_mov_b64 s[68:69], -1
	s_waitcnt vmcnt(14)
	v_add_u32_e32 v17, v0, v15
	s_waitcnt vmcnt(13)
	v_add_u32_e32 v17, v17, v1
	s_waitcnt vmcnt(12)
	v_add_u32_e32 v17, v17, v2
	s_waitcnt vmcnt(11)
	v_add_u32_e32 v17, v17, v3
	s_waitcnt vmcnt(10)
	v_add_u32_e32 v17, v17, v4
	s_waitcnt vmcnt(9)
	v_add_u32_e32 v17, v17, v5
	s_waitcnt vmcnt(8)
	v_add_u32_e32 v17, v17, v6
	s_waitcnt vmcnt(7)
	v_add_u32_e32 v17, v17, v7
	s_waitcnt vmcnt(6)
	v_add_u32_e32 v17, v17, v8
	s_waitcnt vmcnt(5)
	v_add_u32_e32 v17, v17, v9
	s_waitcnt vmcnt(4)
	v_add_u32_e32 v17, v17, v10
	s_waitcnt vmcnt(3)
	v_add_u32_e32 v17, v17, v11
	s_waitcnt vmcnt(2)
	v_add_u32_e32 v17, v17, v12
	s_waitcnt vmcnt(1)
	v_add_u32_e32 v17, v17, v13
	s_waitcnt vmcnt(0)
	v_add_u32_e32 v17, v17, v14
	v_cmp_eq_u32_e32 vcc, s33, v17
	s_cbranch_vccnz .LBB0_2195
	s_and_b32 s1, s0, 0xff
	s_cmp_eq_u32 s1, 0
	s_mov_b64 s[76:77], -1
	s_sleep 4
	s_cbranch_scc1 .LBB0_2200
	s_and_b64 vcc, exec, s[76:77]
	s_cbranch_vccz .LBB0_2195

; __device__ __forceinline__ unsigned xb_ld(unsigned* p)              { return __hip_atomic_load(p, __ATOMIC_RELAXED, __HIP_MEMORY_SCOPE_AGENT); }
; __device__ __forceinline__ void xcd_barrier_complete(unsigned* bar, unsigned x, unsigned& nloc, unsigned& nx) {
;     ...
;     for (;;) {
;         sum = 0u; cnt = 0u; mine = 0u;
; #pragma unroll
;         for (unsigned j = 0; j < 16; ++j) { const unsigned c = xb_ld(&bar[XB_XCNT(j)]); sum += c; cnt += (c > 0u) ? 1u : 0u; mine = (j == x) ? c : mine; }
;         if (sum == G) break;
;         __builtin_amdgcn_s_sleep(1);
;         if ((++sp & 255u) == 0u) { if (xb_ld(&bar[XB_TMO])) break; if (sp > XB_SPIN_CAP) { atomicAdd(&bar[XB_TMO], 1u); break; } }
;     }
.LBB0_2267:
	global_load_dword v15, v16, s[74:75] offset:1024 sc1
	s_waitcnt lgkmcnt(0)
	global_load_dword v0, v16, s[74:75] offset:1280 sc1
	global_load_dword v1, v16, s[74:75] offset:1536 sc1
	global_load_dword v2, v16, s[74:75] offset:1792 sc1
	global_load_dword v3, v16, s[74:75] offset:2048 sc1
	global_load_dword v4, v16, s[74:75] offset:2304 sc1
	global_load_dword v5, v16, s[74:75] offset:2560 sc1
	global_load_dword v6, v16, s[74:75] offset:2816 sc1
	global_load_dword v7, v16, s[74:75] offset:3072 sc1
	global_load_dword v8, v16, s[74:75] offset:3328 sc1
	global_load_dword v9, v16, s[74:75] offset:3584 sc1
	global_load_dword v10, v16, s[74:75] offset:3840 sc1
	global_load_dword v11, v16, s[8:9] sc1
	global_load_dword v12, v16, s[10:11] sc1
	global_load_dword v13, v16, s[16:17] sc1
	global_load_dword v14, v16, s[18:19] sc1
	s_mov_b64 s[54:55], -1
	s_mov_b64 s[62:63], -1
	s_waitcnt vmcnt(14)
	v_add_u32_e32 v17, v0, v15
	s_waitcnt vmcnt(13)
	v_add_u32_e32 v17, v17, v1
	s_waitcnt vmcnt(12)
	v_add_u32_e32 v17, v17, v2
	s_waitcnt vmcnt(11)
	v_add_u32_e32 v17, v17, v3
	s_waitcnt vmcnt(10)
	v_add_u32_e32 v17, v17, v4
	s_waitcnt vmcnt(9)
	v_add_u32_e32 v17, v17, v5
	s_waitcnt vmcnt(8)
	v_add_u32_e32 v17, v17, v6
	s_waitcnt vmcnt(7)
	v_add_u32_e32 v17, v17, v7
	s_waitcnt vmcnt(6)
	v_add_u32_e32 v17, v17, v8
	s_waitcnt vmcnt(5)
	v_add_u32_e32 v17, v17, v9
	s_waitcnt vmcnt(4)
	v_add_u32_e32 v17, v17, v10
	s_waitcnt vmcnt(3)
	v_add_u32_e32 v17, v17, v11
	s_waitcnt vmcnt(2)
	v_add_u32_e32 v17, v17, v12
	s_waitcnt vmcnt(1)
	v_add_u32_e32 v17, v17, v13
	s_waitcnt vmcnt(0)
	v_add_u32_e32 v17, v17, v14
	v_cmp_eq_u32_e32 vcc, s33, v17
	s_cbranch_vccnz .LBB0_2266
	s_and_b32 s1, s0, 0xff
	s_cmp_eq_u32 s1, 0
	s_mov_b64 s[66:67], -1
	s_sleep 4
	s_cbranch_scc1 .LBB0_2271
	s_and_b64 vcc, exec, s[66:67]
	s_cbranch_vccz .LBB0_2266

.LBB0_2285:
	s_and_b32 s1, s0, 0xff
	s_mov_b64 s[66:67], -1
	s_cmp_lg_u32 s1, 0
	s_mov_b64 s[76:77], -1
	s_sleep 4
	s_cbranch_scc0 .LBB0_2288
	s_and_b64 vcc, exec, s[76:77]
	s_cbranch_vccz .LBB0_2284

.LBB0_2302:
	s_and_b32 s1, s0, 0xff
	s_cmp_lg_u32 s1, 0
	s_mov_b64 s[76:77], -1
	s_sleep 4
	s_cbranch_scc0 .LBB0_2305
	s_mov_b64 s[78:79], -1
	s_and_b64 vcc, exec, s[76:77]
	s_cbranch_vccz .LBB0_2301

; __device__ __forceinline__ unsigned xb_ld(unsigned* p)              { return __hip_atomic_load(p, __ATOMIC_RELAXED, __HIP_MEMORY_SCOPE_AGENT); }
; __device__ __forceinline__ void xcd_barrier_complete(unsigned* bar, unsigned x, unsigned& nloc, unsigned& nx) {
;     const unsigned G = gridDim.x;
;     unsigned sum, cnt, mine, sp = 0u;
;     for (;;) {
;         sum = 0u; cnt = 0u; mine = 0u;
; #pragma unroll
;         for (unsigned j = 0; j < 16; ++j) { const unsigned c = xb_ld(&bar[XB_XCNT(j)]); sum += c; cnt += (c > 0u) ? 1u : 0u; mine = (j == x) ? c : mine; }
;         if (sum == G) break;
;         __builtin_amdgcn_s_sleep(1);
;         if ((++sp & 255u) == 0u) { if (xb_ld(&bar[XB_TMO])) break; if (sp > XB_SPIN_CAP) { atomicAdd(&bar[XB_TMO], 1u); break; } }
;     }
;     nloc = mine > 0u ? mine : 1u; nx = cnt > 0u ? cnt : 1u;
; }
.LBB0_2344:
	global_load_dword v15, v16, s[74:75] offset:1024 sc1
	s_waitcnt lgkmcnt(0)
	global_load_dword v0, v16, s[74:75] offset:1280 sc1
	global_load_dword v1, v16, s[74:75] offset:1536 sc1
	global_load_dword v2, v16, s[74:75] offset:1792 sc1
	global_load_dword v3, v16, s[74:75] offset:2048 sc1
	global_load_dword v4, v16, s[74:75] offset:2304 sc1
	global_load_dword v5, v16, s[74:75] offset:2560 sc1
	global_load_dword v6, v16, s[74:75] offset:2816 sc1
	global_load_dword v7, v16, s[74:75] offset:3072 sc1
	global_load_dword v8, v16, s[74:75] offset:3328 sc1
	global_load_dword v9, v16, s[74:75] offset:3584 sc1
	global_load_dword v10, v16, s[74:75] offset:3840 sc1
	global_load_dword v11, v16, s[8:9] sc1
	global_load_dword v12, v16, s[10:11] sc1
	global_load_dword v13, v16, s[18:19] sc1
	global_load_dword v14, v16, s[30:31] sc1
	s_mov_b64 s[54:55], -1
	s_mov_b64 s[62:63], -1
	s_waitcnt vmcnt(14)
	v_add_u32_e32 v17, v0, v15
	s_waitcnt vmcnt(13)
	v_add_u32_e32 v17, v17, v1
	s_waitcnt vmcnt(12)
	v_add_u32_e32 v17, v17, v2
	s_waitcnt vmcnt(11)
	v_add_u32_e32 v17, v17, v3
	s_waitcnt vmcnt(10)
	v_add_u32_e32 v17, v17, v4
	s_waitcnt vmcnt(9)
	v_add_u32_e32 v17, v17, v5
	s_waitcnt vmcnt(8)
	v_add_u32_e32 v17, v17, v6
	s_waitcnt vmcnt(7)
	v_add_u32_e32 v17, v17, v7
	s_waitcnt vmcnt(6)
	v_add_u32_e32 v17, v17, v8
	s_waitcnt vmcnt(5)
	v_add_u32_e32 v17, v17, v9
	s_waitcnt vmcnt(4)
	v_add_u32_e32 v17, v17, v10
	s_waitcnt vmcnt(3)
	v_add_u32_e32 v17, v17, v11
	s_waitcnt vmcnt(2)
	v_add_u32_e32 v17, v17, v12
	s_waitcnt vmcnt(1)
	v_add_u32_e32 v17, v17, v13
	s_waitcnt vmcnt(0)
	v_add_u32_e32 v17, v17, v14
	v_cmp_eq_u32_e32 vcc, s33, v17
	s_cbranch_vccnz .LBB0_2343
	s_and_b32 s1, s0, 0xff
	s_cmp_eq_u32 s1, 0
	s_mov_b64 s[66:67], -1
	s_sleep 4
	s_cbranch_scc1 .LBB0_2348
	s_and_b64 vcc, exec, s[66:67]
	s_cbranch_vccz .LBB0_2343

; __device__ __forceinline__ unsigned xb_ld(unsigned* p)              { return __hip_atomic_load(p, __ATOMIC_RELAXED, __HIP_MEMORY_SCOPE_AGENT); }
; __device__ __forceinline__ void xcd_barrier_complete(unsigned* bar, unsigned x, unsigned& nloc, unsigned& nx) {
;     const unsigned G = gridDim.x;
;     unsigned sum, cnt, mine, sp = 0u;
;     for (;;) {
;         sum = 0u; cnt = 0u; mine = 0u;
; #pragma unroll
;         for (unsigned j = 0; j < 16; ++j) { const unsigned c = xb_ld(&bar[XB_XCNT(j)]); sum += c; cnt += (c > 0u) ? 1u : 0u; mine = (j == x) ? c : mine; }
;         if (sum == G) break;
;         __builtin_amdgcn_s_sleep(1);
;         if ((++sp & 255u) == 0u) { if (xb_ld(&bar[XB_TMO])) break; if (sp > XB_SPIN_CAP) { atomicAdd(&bar[XB_TMO], 1u); break; } }
;     }
;     nloc = mine > 0u ? mine : 1u; nx = cnt > 0u ? cnt : 1u;
; }
.LBB0_2518:
	global_load_dword v15, v16, s[74:75] offset:1024 sc1
	s_waitcnt lgkmcnt(0)
	global_load_dword v0, v16, s[74:75] offset:1280 sc1
	global_load_dword v1, v16, s[74:75] offset:1536 sc1
	global_load_dword v2, v16, s[74:75] offset:1792 sc1
	global_load_dword v3, v16, s[74:75] offset:2048 sc1
	global_load_dword v4, v16, s[74:75] offset:2304 sc1
	global_load_dword v5, v16, s[74:75] offset:2560 sc1
	global_load_dword v6, v16, s[74:75] offset:2816 sc1
	global_load_dword v7, v16, s[74:75] offset:3072 sc1
	global_load_dword v8, v16, s[74:75] offset:3328 sc1
	global_load_dword v9, v16, s[74:75] offset:3584 sc1
	global_load_dword v10, v16, s[74:75] offset:3840 sc1
	global_load_dword v11, v16, s[6:7] sc1
	global_load_dword v12, v16, s[8:9] sc1
	global_load_dword v13, v16, s[10:11] sc1
	global_load_dword v14, v16, s[30:31] sc1
	s_mov_b64 s[54:55], -1
	s_mov_b64 s[62:63], -1
	s_waitcnt vmcnt(14)
	v_add_u32_e32 v17, v0, v15
	s_waitcnt vmcnt(13)
	v_add_u32_e32 v17, v17, v1
	s_waitcnt vmcnt(12)
	v_add_u32_e32 v17, v17, v2
	s_waitcnt vmcnt(11)
	v_add_u32_e32 v17, v17, v3
	s_waitcnt vmcnt(10)
	v_add_u32_e32 v17, v17, v4
	s_waitcnt vmcnt(9)
	v_add_u32_e32 v17, v17, v5
	s_waitcnt vmcnt(8)
	v_add_u32_e32 v17, v17, v6
	s_waitcnt vmcnt(7)
	v_add_u32_e32 v17, v17, v7
	s_waitcnt vmcnt(6)
	v_add_u32_e32 v17, v17, v8
	s_waitcnt vmcnt(5)
	v_add_u32_e32 v17, v17, v9
	s_waitcnt vmcnt(4)
	v_add_u32_e32 v17, v17, v10
	s_waitcnt vmcnt(3)
	v_add_u32_e32 v17, v17, v11
	s_waitcnt vmcnt(2)
	v_add_u32_e32 v17, v17, v12
	s_waitcnt vmcnt(1)
	v_add_u32_e32 v17, v17, v13
	s_waitcnt vmcnt(0)
	v_add_u32_e32 v17, v17, v14
	v_cmp_eq_u32_e32 vcc, s33, v17
	s_cbranch_vccnz .LBB0_2517
	s_and_b32 s3, s2, 0xff
	s_cmp_eq_u32 s3, 0
	s_mov_b64 s[66:67], -1
	s_sleep 4
	s_cbranch_scc1 .LBB0_2522
	s_and_b64 vcc, exec, s[66:67]
	s_cbranch_vccz .LBB0_2517

; __device__ __forceinline__ unsigned xb_ld(unsigned* p)              { return __hip_atomic_load(p, __ATOMIC_RELAXED, __HIP_MEMORY_SCOPE_AGENT); }
; #define XB_SPIN(cond, bar) do { unsigned _sp = 0; while (cond) { __builtin_amdgcn_s_sleep(1); \
;     if ((++_sp & 255u) == 0u) { if (xb_ld(&(bar)[XB_TMO])) break; if (_sp > XB_SPIN_CAP) { atomicAdd(&(bar)[XB_TMO], 1u); break; } } } } while (0)
; __device__ __forceinline__ void xcd_barrier(const XcdBarrier& b) {
;     ...
;             else XB_SPIN(xb_ld(&bar[XB_TOPGEN]) == tg, bar);
.LBB0_2536:
	s_and_b32 s3, s2, 0xff
	s_mov_b64 s[66:67], -1
	s_cmp_lg_u32 s3, 0
	s_mov_b64 s[76:77], -1
	s_sleep 4
	s_cbranch_scc0 .LBB0_2539
	s_and_b64 vcc, exec, s[76:77]
	s_cbranch_vccz .LBB0_2535

; __device__ __forceinline__ unsigned xb_ld(unsigned* p)              { return __hip_atomic_load(p, __ATOMIC_RELAXED, __HIP_MEMORY_SCOPE_AGENT); }
; #define XB_SPIN(cond, bar) do { unsigned _sp = 0; while (cond) { __builtin_amdgcn_s_sleep(1); \
;     if ((++_sp & 255u) == 0u) { if (xb_ld(&(bar)[XB_TMO])) break; if (_sp > XB_SPIN_CAP) { atomicAdd(&(bar)[XB_TMO], 1u); break; } } } } while (0)
; __device__ __forceinline__ void xcd_barrier(const XcdBarrier& b) {
;     ...
;             XB_SPIN(xb_ld(&bar[XB_XGEN(b.x)]) == gen, bar);
.LBB0_2553:
	s_and_b32 s3, s2, 0xff
	s_cmp_lg_u32 s3, 0
	s_mov_b64 s[76:77], -1
	s_sleep 4
	s_cbranch_scc0 .LBB0_2556
	s_mov_b64 s[78:79], -1
	s_and_b64 vcc, exec, s[76:77]
	s_cbranch_vccz .LBB0_2552

; __device__ __forceinline__ unsigned xb_ld(unsigned* p)              { return __hip_atomic_load(p, __ATOMIC_RELAXED, __HIP_MEMORY_SCOPE_AGENT); }
; __device__ __forceinline__ void xcd_barrier_complete(unsigned* bar, unsigned x, unsigned& nloc, unsigned& nx) {
;     const unsigned G = gridDim.x;
;     unsigned sum, cnt, mine, sp = 0u;
;     for (;;) {
;         sum = 0u; cnt = 0u; mine = 0u;
; #pragma unroll
;         for (unsigned j = 0; j < 16; ++j) { const unsigned c = xb_ld(&bar[XB_XCNT(j)]); sum += c; cnt += (c > 0u) ? 1u : 0u; mine = (j == x) ? c : mine; }
;         if (sum == G) break;
;         __builtin_amdgcn_s_sleep(1);
;         if ((++sp & 255u) == 0u) { if (xb_ld(&bar[XB_TMO])) break; if (sp > XB_SPIN_CAP) { atomicAdd(&bar[XB_TMO], 1u); break; } }
;     }
;     nloc = mine > 0u ? mine : 1u; nx = cnt > 0u ? cnt : 1u;
; }
.LBB0_2822:
	global_load_dword v15, v16, s[74:75] offset:1024 sc1
	s_waitcnt lgkmcnt(0)
	global_load_dword v0, v16, s[74:75] offset:1280 sc1
	global_load_dword v1, v16, s[74:75] offset:1536 sc1
	global_load_dword v2, v16, s[74:75] offset:1792 sc1
	global_load_dword v3, v16, s[74:75] offset:2048 sc1
	global_load_dword v4, v16, s[74:75] offset:2304 sc1
	global_load_dword v5, v16, s[74:75] offset:2560 sc1
	global_load_dword v6, v16, s[74:75] offset:2816 sc1
	global_load_dword v7, v16, s[74:75] offset:3072 sc1
	global_load_dword v8, v16, s[74:75] offset:3328 sc1
	global_load_dword v9, v16, s[74:75] offset:3584 sc1
	global_load_dword v10, v16, s[74:75] offset:3840 sc1
	global_load_dword v11, v16, s[6:7] sc1
	global_load_dword v12, v16, s[8:9] sc1
	global_load_dword v13, v16, s[10:11] sc1
	global_load_dword v14, v16, s[12:13] sc1
	s_mov_b64 s[30:31], -1
	s_mov_b64 s[54:55], -1
	s_waitcnt vmcnt(14)
	v_add_u32_e32 v17, v0, v15
	s_waitcnt vmcnt(13)
	v_add_u32_e32 v17, v17, v1
	s_waitcnt vmcnt(12)
	v_add_u32_e32 v17, v17, v2
	s_waitcnt vmcnt(11)
	v_add_u32_e32 v17, v17, v3
	s_waitcnt vmcnt(10)
	v_add_u32_e32 v17, v17, v4
	s_waitcnt vmcnt(9)
	v_add_u32_e32 v17, v17, v5
	s_waitcnt vmcnt(8)
	v_add_u32_e32 v17, v17, v6
	s_waitcnt vmcnt(7)
	v_add_u32_e32 v17, v17, v7
	s_waitcnt vmcnt(6)
	v_add_u32_e32 v17, v17, v8
	s_waitcnt vmcnt(5)
	v_add_u32_e32 v17, v17, v9
	s_waitcnt vmcnt(4)
	v_add_u32_e32 v17, v17, v10
	s_waitcnt vmcnt(3)
	v_add_u32_e32 v17, v17, v11
	s_waitcnt vmcnt(2)
	v_add_u32_e32 v17, v17, v12
	s_waitcnt vmcnt(1)
	v_add_u32_e32 v17, v17, v13
	s_waitcnt vmcnt(0)
	v_add_u32_e32 v17, v17, v14
	v_cmp_eq_u32_e32 vcc, s33, v17
	s_cbranch_vccnz .LBB0_2821
	s_and_b32 s3, s2, 0xff
	s_cmp_eq_u32 s3, 0
	s_mov_b64 s[60:61], -1
	s_sleep 4
	s_cbranch_scc1 .LBB0_2826
	s_and_b64 vcc, exec, s[60:61]
	s_cbranch_vccz .LBB0_2821

; __device__ __forceinline__ unsigned xb_ld(unsigned* p)              { return __hip_atomic_load(p, __ATOMIC_RELAXED, __HIP_MEMORY_SCOPE_AGENT); }
; #define XB_SPIN(cond, bar) do { unsigned _sp = 0; while (cond) { __builtin_amdgcn_s_sleep(1); \
;     if ((++_sp & 255u) == 0u) { if (xb_ld(&(bar)[XB_TMO])) break; if (_sp > XB_SPIN_CAP) { atomicAdd(&(bar)[XB_TMO], 1u); break; } } } } while (0)
; __device__ __forceinline__ void xcd_barrier(const XcdBarrier& b) {
;     ...
;             else XB_SPIN(xb_ld(&bar[XB_TOPGEN]) == tg, bar);
.LBB0_2840:
	s_and_b32 s3, s2, 0xff
	s_mov_b64 s[60:61], -1
	s_cmp_lg_u32 s3, 0
	s_mov_b64 s[64:65], -1
	s_sleep 4
	s_cbranch_scc0 .LBB0_2843
	s_and_b64 vcc, exec, s[64:65]
	s_cbranch_vccz .LBB0_2839

; __device__ __forceinline__ unsigned xb_ld(unsigned* p)              { return __hip_atomic_load(p, __ATOMIC_RELAXED, __HIP_MEMORY_SCOPE_AGENT); }
; #define XB_SPIN(cond, bar) do { unsigned _sp = 0; while (cond) { __builtin_amdgcn_s_sleep(1); \
;     if ((++_sp & 255u) == 0u) { if (xb_ld(&(bar)[XB_TMO])) break; if (_sp > XB_SPIN_CAP) { atomicAdd(&(bar)[XB_TMO], 1u); break; } } } } while (0)
; __device__ __forceinline__ void xcd_barrier(const XcdBarrier& b) {
;     ...
;             XB_SPIN(xb_ld(&bar[XB_XGEN(b.x)]) == gen, bar);
.LBB0_2857:
	s_and_b32 s3, s2, 0xff
	s_cmp_lg_u32 s3, 0
	s_mov_b64 s[64:65], -1
	s_sleep 4
	s_cbranch_scc0 .LBB0_2860
	s_mov_b64 s[66:67], -1
	s_and_b64 vcc, exec, s[64:65]
	s_cbranch_vccz .LBB0_2856

; __device__ __forceinline__ unsigned xb_ld(unsigned* p)              { return __hip_atomic_load(p, __ATOMIC_RELAXED, __HIP_MEMORY_SCOPE_AGENT); }
; __device__ __forceinline__ void xcd_barrier_complete(unsigned* bar, unsigned x, unsigned& nloc, unsigned& nx) {
;     const unsigned G = gridDim.x;
;     unsigned sum, cnt, mine, sp = 0u;
;     for (;;) {
;         sum = 0u; cnt = 0u; mine = 0u;
; #pragma unroll
;         for (unsigned j = 0; j < 16; ++j) { const unsigned c = xb_ld(&bar[XB_XCNT(j)]); sum += c; cnt += (c > 0u) ? 1u : 0u; mine = (j == x) ? c : mine; }
;         if (sum == G) break;
;         __builtin_amdgcn_s_sleep(1);
;         if ((++sp & 255u) == 0u) { if (xb_ld(&bar[XB_TMO])) break; if (sp > XB_SPIN_CAP) { atomicAdd(&bar[XB_TMO], 1u); break; } }
;     }
;     nloc = mine > 0u ? mine : 1u; nx = cnt > 0u ? cnt : 1u;
; }
.LBB0_3078:
	global_load_dword v15, v16, s[74:75] offset:1024 sc1
	s_waitcnt lgkmcnt(0)
	global_load_dword v0, v16, s[74:75] offset:1280 sc1
	global_load_dword v1, v16, s[74:75] offset:1536 sc1
	global_load_dword v2, v16, s[74:75] offset:1792 sc1
	global_load_dword v3, v16, s[74:75] offset:2048 sc1
	global_load_dword v4, v16, s[74:75] offset:2304 sc1
	global_load_dword v5, v16, s[74:75] offset:2560 sc1
	global_load_dword v6, v16, s[74:75] offset:2816 sc1
	global_load_dword v7, v16, s[74:75] offset:3072 sc1
	global_load_dword v8, v16, s[74:75] offset:3328 sc1
	global_load_dword v9, v16, s[74:75] offset:3584 sc1
	global_load_dword v10, v16, s[74:75] offset:3840 sc1
	global_load_dword v11, v16, s[6:7] sc1
	global_load_dword v12, v16, s[8:9] sc1
	global_load_dword v13, v16, s[10:11] sc1
	global_load_dword v14, v16, s[12:13] sc1
	s_mov_b64 s[30:31], -1
	s_mov_b64 s[52:53], -1
	s_waitcnt vmcnt(14)
	v_add_u32_e32 v17, v0, v15
	s_waitcnt vmcnt(13)
	v_add_u32_e32 v17, v17, v1
	s_waitcnt vmcnt(12)
	v_add_u32_e32 v17, v17, v2
	s_waitcnt vmcnt(11)
	v_add_u32_e32 v17, v17, v3
	s_waitcnt vmcnt(10)
	v_add_u32_e32 v17, v17, v4
	s_waitcnt vmcnt(9)
	v_add_u32_e32 v17, v17, v5
	s_waitcnt vmcnt(8)
	v_add_u32_e32 v17, v17, v6
	s_waitcnt vmcnt(7)
	v_add_u32_e32 v17, v17, v7
	s_waitcnt vmcnt(6)
	v_add_u32_e32 v17, v17, v8
	s_waitcnt vmcnt(5)
	v_add_u32_e32 v17, v17, v9
	s_waitcnt vmcnt(4)
	v_add_u32_e32 v17, v17, v10
	s_waitcnt vmcnt(3)
	v_add_u32_e32 v17, v17, v11
	s_waitcnt vmcnt(2)
	v_add_u32_e32 v17, v17, v12
	s_waitcnt vmcnt(1)
	v_add_u32_e32 v17, v17, v13
	s_waitcnt vmcnt(0)
	v_add_u32_e32 v17, v17, v14
	v_cmp_eq_u32_e32 vcc, s33, v17
	s_cbranch_vccnz .LBB0_3077
	s_and_b32 s3, s2, 0xff
	s_cmp_eq_u32 s3, 0
	s_mov_b64 s[54:55], -1
	s_sleep 4
	s_cbranch_scc1 .LBB0_3082
	s_and_b64 vcc, exec, s[54:55]
	s_cbranch_vccz .LBB0_3077

; __device__ __forceinline__ unsigned xb_ld(unsigned* p)              { return __hip_atomic_load(p, __ATOMIC_RELAXED, __HIP_MEMORY_SCOPE_AGENT); }
; #define XB_SPIN(cond, bar) do { unsigned _sp = 0; while (cond) { __builtin_amdgcn_s_sleep(1); \
;     if ((++_sp & 255u) == 0u) { if (xb_ld(&(bar)[XB_TMO])) break; if (_sp > XB_SPIN_CAP) { atomicAdd(&(bar)[XB_TMO], 1u); break; } } } } while (0)
; __device__ __forceinline__ void xcd_barrier(const XcdBarrier& b) {
;     ...
;             else XB_SPIN(xb_ld(&bar[XB_TOPGEN]) == tg, bar);
.LBB0_3096:
	s_and_b32 s3, s2, 0xff
	s_mov_b64 s[54:55], -1
	s_cmp_lg_u32 s3, 0
	s_mov_b64 s[62:63], -1
	s_sleep 4
	s_cbranch_scc0 .LBB0_3099
	s_and_b64 vcc, exec, s[62:63]
	s_cbranch_vccz .LBB0_3095

; __device__ __forceinline__ unsigned xb_ld(unsigned* p)              { return __hip_atomic_load(p, __ATOMIC_RELAXED, __HIP_MEMORY_SCOPE_AGENT); }
; #define XB_SPIN(cond, bar) do { unsigned _sp = 0; while (cond) { __builtin_amdgcn_s_sleep(1); \
;     if ((++_sp & 255u) == 0u) { if (xb_ld(&(bar)[XB_TMO])) break; if (_sp > XB_SPIN_CAP) { atomicAdd(&(bar)[XB_TMO], 1u); break; } } } } while (0)
; __device__ __forceinline__ void xcd_barrier(const XcdBarrier& b) {
;     ...
;             XB_SPIN(xb_ld(&bar[XB_XGEN(b.x)]) == gen, bar);
.LBB0_3113:
	s_and_b32 s3, s2, 0xff
	s_cmp_lg_u32 s3, 0
	s_mov_b64 s[62:63], -1
	s_sleep 4
	s_cbranch_scc0 .LBB0_3116
	s_mov_b64 s[64:65], -1
	s_and_b64 vcc, exec, s[62:63]
	s_cbranch_vccz .LBB0_3112

; __device__ __forceinline__ unsigned xb_ld(unsigned* p)              { return __hip_atomic_load(p, __ATOMIC_RELAXED, __HIP_MEMORY_SCOPE_AGENT); }
; __device__ __forceinline__ void xcd_barrier_complete(unsigned* bar, unsigned x, unsigned& nloc, unsigned& nx) {
;     const unsigned G = gridDim.x;
;     unsigned sum, cnt, mine, sp = 0u;
;     for (;;) {
;         sum = 0u; cnt = 0u; mine = 0u;
; #pragma unroll
;         for (unsigned j = 0; j < 16; ++j) { const unsigned c = xb_ld(&bar[XB_XCNT(j)]); sum += c; cnt += (c > 0u) ? 1u : 0u; mine = (j == x) ? c : mine; }
;         if (sum == G) break;
;         __builtin_amdgcn_s_sleep(1);
;         if ((++sp & 255u) == 0u) { if (xb_ld(&bar[XB_TMO])) break; if (sp > XB_SPIN_CAP) { atomicAdd(&bar[XB_TMO], 1u); break; } }
;     }
;     nloc = mine > 0u ? mine : 1u; nx = cnt > 0u ? cnt : 1u;
; }
.LBB0_3713:
	global_load_dword v15, v16, s[74:75] offset:1024 sc1
	s_waitcnt lgkmcnt(0)
	global_load_dword v0, v16, s[74:75] offset:1280 sc1
	global_load_dword v1, v16, s[74:75] offset:1536 sc1
	global_load_dword v2, v16, s[74:75] offset:1792 sc1
	global_load_dword v3, v16, s[74:75] offset:2048 sc1
	global_load_dword v4, v16, s[74:75] offset:2304 sc1
	global_load_dword v5, v16, s[74:75] offset:2560 sc1
	global_load_dword v6, v16, s[74:75] offset:2816 sc1
	global_load_dword v7, v16, s[74:75] offset:3072 sc1
	global_load_dword v8, v16, s[74:75] offset:3328 sc1
	global_load_dword v9, v16, s[74:75] offset:3584 sc1
	global_load_dword v10, v16, s[74:75] offset:3840 sc1
	global_load_dword v11, v16, s[8:9] sc1
	global_load_dword v12, v16, s[10:11] sc1
	global_load_dword v13, v16, s[12:13] sc1
	global_load_dword v14, v16, s[18:19] sc1
	s_mov_b64 s[30:31], -1
	s_mov_b64 s[52:53], -1
	s_waitcnt vmcnt(14)
	v_add_u32_e32 v17, v0, v15
	s_waitcnt vmcnt(13)
	v_add_u32_e32 v17, v17, v1
	s_waitcnt vmcnt(12)
	v_add_u32_e32 v17, v17, v2
	s_waitcnt vmcnt(11)
	v_add_u32_e32 v17, v17, v3
	s_waitcnt vmcnt(10)
	v_add_u32_e32 v17, v17, v4
	s_waitcnt vmcnt(9)
	v_add_u32_e32 v17, v17, v5
	s_waitcnt vmcnt(8)
	v_add_u32_e32 v17, v17, v6
	s_waitcnt vmcnt(7)
	v_add_u32_e32 v17, v17, v7
	s_waitcnt vmcnt(6)
	v_add_u32_e32 v17, v17, v8
	s_waitcnt vmcnt(5)
	v_add_u32_e32 v17, v17, v9
	s_waitcnt vmcnt(4)
	v_add_u32_e32 v17, v17, v10
	s_waitcnt vmcnt(3)
	v_add_u32_e32 v17, v17, v11
	s_waitcnt vmcnt(2)
	v_add_u32_e32 v17, v17, v12
	s_waitcnt vmcnt(1)
	v_add_u32_e32 v17, v17, v13
	s_waitcnt vmcnt(0)
	v_add_u32_e32 v17, v17, v14
	v_cmp_eq_u32_e32 vcc, s33, v17
	s_cbranch_vccnz .LBB0_3712
	s_and_b32 s3, s2, 0xff
	s_cmp_eq_u32 s3, 0
	s_mov_b64 s[54:55], -1
	s_sleep 4
	s_cbranch_scc1 .LBB0_3717
	s_and_b64 vcc, exec, s[54:55]
	s_cbranch_vccz .LBB0_3712

; __device__ __forceinline__ unsigned xb_ld(unsigned* p)              { return __hip_atomic_load(p, __ATOMIC_RELAXED, __HIP_MEMORY_SCOPE_AGENT); }
; __device__ __forceinline__ void xcd_barrier_complete(unsigned* bar, unsigned x, unsigned& nloc, unsigned& nx) {
;     const unsigned G = gridDim.x;
;     unsigned sum, cnt, mine, sp = 0u;
;     for (;;) {
;         sum = 0u; cnt = 0u; mine = 0u;
; #pragma unroll
;         for (unsigned j = 0; j < 16; ++j) { const unsigned c = xb_ld(&bar[XB_XCNT(j)]); sum += c; cnt += (c > 0u) ? 1u : 0u; mine = (j == x) ? c : mine; }
;         if (sum == G) break;
;         __builtin_amdgcn_s_sleep(1);
;         if ((++sp & 255u) == 0u) { if (xb_ld(&bar[XB_TMO])) break; if (sp > XB_SPIN_CAP) { atomicAdd(&bar[XB_TMO], 1u); break; } }
;     }
;     nloc = mine > 0u ? mine : 1u; nx = cnt > 0u ? cnt : 1u;
; }
.LBB0_4126:
	global_load_dword v15, v16, s[74:75] offset:1024 sc1
	s_waitcnt lgkmcnt(0)
	global_load_dword v0, v16, s[74:75] offset:1280 sc1
	global_load_dword v1, v16, s[74:75] offset:1536 sc1
	global_load_dword v2, v16, s[74:75] offset:1792 sc1
	global_load_dword v3, v16, s[74:75] offset:2048 sc1
	global_load_dword v4, v16, s[74:75] offset:2304 sc1
	global_load_dword v5, v16, s[74:75] offset:2560 sc1
	global_load_dword v6, v16, s[74:75] offset:2816 sc1
	global_load_dword v7, v16, s[74:75] offset:3072 sc1
	global_load_dword v8, v16, s[74:75] offset:3328 sc1
	global_load_dword v9, v16, s[74:75] offset:3584 sc1
	global_load_dword v10, v16, s[74:75] offset:3840 sc1
	global_load_dword v11, v16, s[6:7] sc1
	global_load_dword v12, v16, s[8:9] sc1
	global_load_dword v13, v16, s[10:11] sc1
	global_load_dword v14, v16, s[12:13] sc1
	s_mov_b64 s[18:19], -1
	s_mov_b64 s[20:21], -1
	s_waitcnt vmcnt(14)
	v_add_u32_e32 v17, v0, v15
	s_waitcnt vmcnt(13)
	v_add_u32_e32 v17, v17, v1
	s_waitcnt vmcnt(12)
	v_add_u32_e32 v17, v17, v2
	s_waitcnt vmcnt(11)
	v_add_u32_e32 v17, v17, v3
	s_waitcnt vmcnt(10)
	v_add_u32_e32 v17, v17, v4
	s_waitcnt vmcnt(9)
	v_add_u32_e32 v17, v17, v5
	s_waitcnt vmcnt(8)
	v_add_u32_e32 v17, v17, v6
	s_waitcnt vmcnt(7)
	v_add_u32_e32 v17, v17, v7
	s_waitcnt vmcnt(6)
	v_add_u32_e32 v17, v17, v8
	s_waitcnt vmcnt(5)
	v_add_u32_e32 v17, v17, v9
	s_waitcnt vmcnt(4)
	v_add_u32_e32 v17, v17, v10
	s_waitcnt vmcnt(3)
	v_add_u32_e32 v17, v17, v11
	s_waitcnt vmcnt(2)
	v_add_u32_e32 v17, v17, v12
	s_waitcnt vmcnt(1)
	v_add_u32_e32 v17, v17, v13
	s_waitcnt vmcnt(0)
	v_add_u32_e32 v17, v17, v14
	v_cmp_eq_u32_e32 vcc, s33, v17
	s_cbranch_vccnz .LBB0_4125
	s_and_b32 s3, s2, 0xff
	s_cmp_eq_u32 s3, 0
	s_mov_b64 s[22:23], -1
	s_sleep 4
	s_cbranch_scc1 .LBB0_4130
	s_and_b64 vcc, exec, s[22:23]
	s_cbranch_vccz .LBB0_4125

; __device__ __forceinline__ unsigned xb_ld(unsigned* p)              { return __hip_atomic_load(p, __ATOMIC_RELAXED, __HIP_MEMORY_SCOPE_AGENT); }
; #define XB_SPIN(cond, bar) do { unsigned _sp = 0; while (cond) { __builtin_amdgcn_s_sleep(1); \
;     if ((++_sp & 255u) == 0u) { if (xb_ld(&(bar)[XB_TMO])) break; if (_sp > XB_SPIN_CAP) { atomicAdd(&(bar)[XB_TMO], 1u); break; } } } } while (0)
; __device__ __forceinline__ void xcd_barrier(const XcdBarrier& b) {
;     ...
;             else XB_SPIN(xb_ld(&bar[XB_TOPGEN]) == tg, bar);
.LBB0_4144:
	s_and_b32 s3, s2, 0xff
	s_mov_b64 s[22:23], -1
	s_cmp_lg_u32 s3, 0
	s_mov_b64 s[28:29], -1
	s_sleep 4
	s_cbranch_scc0 .LBB0_4147
	s_and_b64 vcc, exec, s[28:29]
	s_cbranch_vccz .LBB0_4143

; __device__ __forceinline__ unsigned xb_ld(unsigned* p)              { return __hip_atomic_load(p, __ATOMIC_RELAXED, __HIP_MEMORY_SCOPE_AGENT); }
; #define XB_SPIN(cond, bar) do { unsigned _sp = 0; while (cond) { __builtin_amdgcn_s_sleep(1); \
;     if ((++_sp & 255u) == 0u) { if (xb_ld(&(bar)[XB_TMO])) break; if (_sp > XB_SPIN_CAP) { atomicAdd(&(bar)[XB_TMO], 1u); break; } } } } while (0)
; __device__ __forceinline__ void xcd_barrier(const XcdBarrier& b) {
;     ...
;             XB_SPIN(xb_ld(&bar[XB_XGEN(b.x)]) == gen, bar);
.LBB0_4161:
	s_and_b32 s3, s2, 0xff
	s_cmp_lg_u32 s3, 0
	s_mov_b64 s[28:29], -1
	s_sleep 4
	s_cbranch_scc0 .LBB0_4164
	s_mov_b64 s[30:31], -1
	s_and_b64 vcc, exec, s[28:29]
	s_cbranch_vccz .LBB0_4160

; __device__ __forceinline__ unsigned xb_ld(unsigned* p)              { return __hip_atomic_load(p, __ATOMIC_RELAXED, __HIP_MEMORY_SCOPE_AGENT); }
; #define XB_SPIN(cond, bar) do { unsigned _sp = 0; while (cond) { __builtin_amdgcn_s_sleep(1); \
;     if ((++_sp & 255u) == 0u) { if (xb_ld(&(bar)[XB_TMO])) break; if (_sp > XB_SPIN_CAP) { atomicAdd(&(bar)[XB_TMO], 1u); break; } } } } while (0)
; __device__ __forceinline__ void xcd_barrier(const XcdBarrier& b) {
;     ...
;             else XB_SPIN(xb_ld(&bar[XB_TOPGEN]) == tg, bar);
.LBB0_4316:
	s_and_b32 s3, s2, 0xff
	s_mov_b64 s[22:23], -1
	s_cmp_lg_u32 s3, 0
	s_mov_b64 s[26:27], -1
	s_sleep 4
	s_cbranch_scc0 .LBB0_4319
	s_and_b64 vcc, exec, s[26:27]
	s_cbranch_vccz .LBB0_4315

; __device__ __forceinline__ unsigned xb_ld(unsigned* p)              { return __hip_atomic_load(p, __ATOMIC_RELAXED, __HIP_MEMORY_SCOPE_AGENT); }
; #define XB_SPIN(cond, bar) do { unsigned _sp = 0; while (cond) { __builtin_amdgcn_s_sleep(1); \
;     if ((++_sp & 255u) == 0u) { if (xb_ld(&(bar)[XB_TMO])) break; if (_sp > XB_SPIN_CAP) { atomicAdd(&(bar)[XB_TMO], 1u); break; } } } } while (0)
; __device__ __forceinline__ void xcd_barrier(const XcdBarrier& b) {
;     ...
;             XB_SPIN(xb_ld(&bar[XB_XGEN(b.x)]) == gen, bar);
.LBB0_4333:
	s_and_b32 s3, s2, 0xff
	s_cmp_lg_u32 s3, 0
	s_mov_b64 s[26:27], -1
	s_sleep 4
	s_cbranch_scc0 .LBB0_4336
	s_mov_b64 s[28:29], -1
	s_and_b64 vcc, exec, s[26:27]
	s_cbranch_vccz .LBB0_4332

; __device__ __forceinline__ unsigned xb_ld(unsigned* p)              { return __hip_atomic_load(p, __ATOMIC_RELAXED, __HIP_MEMORY_SCOPE_AGENT); }
; __device__ __forceinline__ void xcd_barrier_complete(unsigned* bar, unsigned x, unsigned& nloc, unsigned& nx) {
;     const unsigned G = gridDim.x;
;     unsigned sum, cnt, mine, sp = 0u;
;     for (;;) {
;         sum = 0u; cnt = 0u; mine = 0u;
; #pragma unroll
;         for (unsigned j = 0; j < 16; ++j) { const unsigned c = xb_ld(&bar[XB_XCNT(j)]); sum += c; cnt += (c > 0u) ? 1u : 0u; mine = (j == x) ? c : mine; }
;         if (sum == G) break;
;         __builtin_amdgcn_s_sleep(1);
;         if ((++sp & 255u) == 0u) { if (xb_ld(&bar[XB_TMO])) break; if (sp > XB_SPIN_CAP) { atomicAdd(&bar[XB_TMO], 1u); break; } }
;     }
;     nloc = mine > 0u ? mine : 1u; nx = cnt > 0u ? cnt : 1u;
; }
.LBB0_4574:
	global_load_dword v15, v16, s[74:75] offset:1024 sc1
	s_waitcnt lgkmcnt(0)
	global_load_dword v0, v16, s[74:75] offset:1280 sc1
	global_load_dword v1, v16, s[74:75] offset:1536 sc1
	global_load_dword v2, v16, s[74:75] offset:1792 sc1
	global_load_dword v3, v16, s[74:75] offset:2048 sc1
	global_load_dword v4, v16, s[74:75] offset:2304 sc1
	global_load_dword v5, v16, s[74:75] offset:2560 sc1
	global_load_dword v6, v16, s[74:75] offset:2816 sc1
	global_load_dword v7, v16, s[74:75] offset:3072 sc1
	global_load_dword v8, v16, s[74:75] offset:3328 sc1
	global_load_dword v9, v16, s[74:75] offset:3584 sc1
	global_load_dword v10, v16, s[74:75] offset:3840 sc1
	global_load_dword v11, v16, s[2:3] sc1
	global_load_dword v12, v16, s[4:5] sc1
	global_load_dword v13, v16, s[6:7] sc1
	global_load_dword v14, v16, s[8:9] sc1
	s_mov_b64 s[10:11], -1
	s_mov_b64 s[12:13], -1
	s_waitcnt vmcnt(14)
	v_add_u32_e32 v17, v0, v15
	s_waitcnt vmcnt(13)
	v_add_u32_e32 v17, v17, v1
	s_waitcnt vmcnt(12)
	v_add_u32_e32 v17, v17, v2
	s_waitcnt vmcnt(11)
	v_add_u32_e32 v17, v17, v3
	s_waitcnt vmcnt(10)
	v_add_u32_e32 v17, v17, v4
	s_waitcnt vmcnt(9)
	v_add_u32_e32 v17, v17, v5
	s_waitcnt vmcnt(8)
	v_add_u32_e32 v17, v17, v6
	s_waitcnt vmcnt(7)
	v_add_u32_e32 v17, v17, v7
	s_waitcnt vmcnt(6)
	v_add_u32_e32 v17, v17, v8
	s_waitcnt vmcnt(5)
	v_add_u32_e32 v17, v17, v9
	s_waitcnt vmcnt(4)
	v_add_u32_e32 v17, v17, v10
	s_waitcnt vmcnt(3)
	v_add_u32_e32 v17, v17, v11
	s_waitcnt vmcnt(2)
	v_add_u32_e32 v17, v17, v12
	s_waitcnt vmcnt(1)
	v_add_u32_e32 v17, v17, v13
	s_waitcnt vmcnt(0)
	v_add_u32_e32 v17, v17, v14
	v_cmp_eq_u32_e32 vcc, s33, v17
	s_cbranch_vccnz .LBB0_4573
	s_and_b32 s10, s18, 0xff
	s_cmp_eq_u32 s10, 0
	s_mov_b64 s[10:11], -1
	s_mov_b64 s[14:15], -1
	s_sleep 4
	s_cbranch_scc1 .LBB0_4578
	s_and_b64 vcc, exec, s[14:15]
	s_cbranch_vccz .LBB0_4573

; __device__ __forceinline__ unsigned xb_ld(unsigned* p)              { return __hip_atomic_load(p, __ATOMIC_RELAXED, __HIP_MEMORY_SCOPE_AGENT); }
; #define XB_SPIN(cond, bar) do { unsigned _sp = 0; while (cond) { __builtin_amdgcn_s_sleep(1); \
;     if ((++_sp & 255u) == 0u) { if (xb_ld(&(bar)[XB_TMO])) break; if (_sp > XB_SPIN_CAP) { atomicAdd(&(bar)[XB_TMO], 1u); break; } } } } while (0)
; __device__ __forceinline__ void xcd_barrier(const XcdBarrier& b) {
;     ...
;             else XB_SPIN(xb_ld(&bar[XB_TOPGEN]) == tg, bar);
.LBB0_4592:
	s_and_b32 s18, s22, 0xff
	s_mov_b64 s[14:15], -1
	s_cmp_lg_u32 s18, 0
	s_mov_b64 s[20:21], -1
	s_sleep 4
	s_cbranch_scc0 .LBB0_4595
	s_and_b64 vcc, exec, s[20:21]
	s_cbranch_vccz .LBB0_4591

; __device__ __forceinline__ unsigned xb_ld(unsigned* p)              { return __hip_atomic_load(p, __ATOMIC_RELAXED, __HIP_MEMORY_SCOPE_AGENT); }
; #define XB_SPIN(cond, bar) do { unsigned _sp = 0; while (cond) { __builtin_amdgcn_s_sleep(1); \
;     if ((++_sp & 255u) == 0u) { if (xb_ld(&(bar)[XB_TMO])) break; if (_sp > XB_SPIN_CAP) { atomicAdd(&(bar)[XB_TMO], 1u); break; } } } } while (0)
; __device__ __forceinline__ void xcd_barrier(const XcdBarrier& b) {
;     ...
;             XB_SPIN(xb_ld(&bar[XB_XGEN(b.x)]) == gen, bar);
.LBB0_4609:
	s_and_b32 s18, s24, 0xff
	s_cmp_lg_u32 s18, 0
	s_mov_b64 s[20:21], -1
	s_sleep 4
	s_cbranch_scc0 .LBB0_4612
	s_mov_b64 s[22:23], -1
	s_and_b64 vcc, exec, s[20:21]
	s_cbranch_vccz .LBB0_4608
